# v18 plus dual consumer loops: packed loop for long (critical) items, LDS-light DPP loop for short items to cut LDS contention
# speedup vs baseline: 1.0030x; 1.0027x over previous
.LBB0_385:
	s_cmp_ge_u32 s0, s77
	s_cbranch_scc1 .LBB0_384
	v_cndmask_b32_e64 v64, 0, 1, s[90:91]
	s_lshl_b32 s1, s0, 1
	v_lshl_add_u32 v152, v64, 12, v200
	v_and_or_b32 v64, s1, 2, v171
	v_mul_u32_u24_e32 v204, 0x3000, v64
	s_cmp_lt_i32 s18, 32
	s_cbranch_scc1 .Lcons_short_pre
	ds_read_b128 v[64:67], v204 offset:256
	ds_read_b128 v[68:71], v204 offset:272
	ds_read_b128 v[72:75], v204 offset:288
	ds_read_b128 v[76:79], v204 offset:304
	ds_read_b128 v[80:83], v204 offset:320
	ds_read_b128 v[84:87], v204 offset:336
	ds_read_b128 v[88:91], v204 offset:352
	ds_read_b128 v[92:95], v204 offset:368
	ds_read_b128 v[96:99], v204 offset:384
	ds_read_b128 v[100:103], v204 offset:400
	ds_read_b128 v[104:107], v204 offset:416
	ds_read_b128 v[108:111], v204 offset:432
	ds_read_b128 v[112:115], v204 offset:448
	ds_read_b128 v[116:119], v204 offset:464
	ds_read_b128 v[120:123], v204 offset:480
	ds_read_b128 v[124:127], v204 offset:496
	ds_read_b128 v[128:131], v204 offset:0
	ds_read_b128 v[132:135], v204 offset:16
	ds_read_b128 v[136:139], v204 offset:32
	ds_read_b128 v[140:143], v204 offset:48
	s_waitcnt vmcnt(0)
	s_mov_b32 s1, 0

.Lcons_short_pre:
	ds_read_b128 v[64:67], v204 offset:256
	ds_read_b128 v[68:71], v204 offset:272
	ds_read_b128 v[72:75], v204 offset:288
	ds_read_b128 v[76:79], v204 offset:304
	ds_read_b128 v[80:83], v204 offset:320
	ds_read_b128 v[84:87], v204 offset:336
	ds_read_b128 v[88:91], v204 offset:352
	ds_read_b128 v[92:95], v204 offset:368
	s_waitcnt vmcnt(0)
	s_mov_b32 s1, 0
.Lcons_short_loop:
	v_add_u32_e32 v96, v204, v173
	ds_read_b32 v205, v96 offset:1280
	ds_read_b128 v[96:99], v204 offset:384
	ds_read_b128 v[100:103], v204 offset:400
	ds_read_b128 v[104:107], v204 offset:416
	ds_read_b128 v[108:111], v204 offset:432
	ds_read_b128 v[124:127], v204 offset:448
	ds_read_b128 v[132:135], v204 offset:464
	ds_read_b128 v[136:139], v204 offset:480
	ds_read_b128 v[140:143], v204 offset:496
	s_waitcnt lgkmcnt(12)
	v_pk_fma_f32 v[66:67], v[2:3], v[66:67], 0 op_sel_hi:[1,1,0]
	v_pk_fma_f32 v[64:65], v[0:1], v[64:65], 0 op_sel_hi:[1,1,0]
	v_pk_fma_f32 v[66:67], v[6:7], v[70:71], v[66:67]
	v_pk_fma_f32 v[64:65], v[4:5], v[68:69], v[64:65]
	v_pk_fma_f32 v[66:67], v[10:11], v[74:75], v[66:67]
	v_pk_fma_f32 v[64:65], v[8:9], v[72:73], v[64:65]
	v_pk_fma_f32 v[66:67], v[14:15], v[78:79], v[66:67]
	v_pk_fma_f32 v[64:65], v[12:13], v[76:77], v[64:65]
	v_add_u32_e32 v207, v204, v201
	ds_read_b128 v[208:211], v207 offset:512
	ds_read_b128 v[212:215], v207 offset:768
	ds_read_b128 v[216:219], v204
	ds_read_b128 v[220:223], v204 offset:16
	ds_read_b128 v[224:227], v204 offset:32
	ds_read_b128 v[228:231], v204 offset:48
	s_waitcnt lgkmcnt(13)
	v_pk_fma_f32 v[64:65], v[16:17], v[80:81], v[64:65]
	v_pk_fma_f32 v[66:67], v[18:19], v[82:83], v[66:67]
	v_pk_fma_f32 v[64:65], v[20:21], v[84:85], v[64:65]
	v_pk_fma_f32 v[66:67], v[22:23], v[86:87], v[66:67]
	v_pk_fma_f32 v[64:65], v[24:25], v[88:89], v[64:65]
	v_pk_fma_f32 v[66:67], v[26:27], v[90:91], v[66:67]
	v_pk_fma_f32 v[64:65], v[28:29], v[92:93], v[64:65]
	v_pk_fma_f32 v[88:89], v[30:31], v[94:95], v[66:67]
	v_pk_fma_f32 v[64:65], v[32:33], v[96:97], v[64:65]
	ds_read_b128 v[68:71], v207 offset:576
	ds_read_b128 v[72:75], v207 offset:832
	ds_read_b128 v[128:131], v204 offset:64
	ds_read_b128 v[120:123], v204 offset:80
	ds_read_b128 v[116:119], v204 offset:96
	ds_read_b128 v[112:115], v204 offset:112
	s_waitcnt lgkmcnt(14)
	v_pk_fma_f32 v[64:65], v[36:37], v[100:101], v[64:65]
	v_pk_fma_f32 v[88:89], v[34:35], v[98:99], v[88:89]
	v_pk_fma_f32 v[64:65], v[40:41], v[104:105], v[64:65]
	v_pk_fma_f32 v[88:89], v[38:39], v[102:103], v[88:89]
	v_pk_fma_f32 v[90:91], v[44:45], v[108:109], v[64:65]
	ds_read_b128 v[76:79], v204 offset:1024
	ds_read_b128 v[80:83], v204 offset:1040
	ds_read_b128 v[84:87], v204 offset:1056
	ds_read_b128 v[64:67], v204 offset:1072
	v_pk_fma_f32 v[88:89], v[42:43], v[106:107], v[88:89]
	v_pk_fma_f32 v[90:91], v[48:49], v[124:125], v[90:91]
	v_pk_fma_f32 v[88:89], v[46:47], v[110:111], v[88:89]
	v_pk_fma_f32 v[90:91], v[52:53], v[132:133], v[90:91]
	v_pk_fma_f32 v[88:89], v[50:51], v[126:127], v[88:89]
	s_waitcnt lgkmcnt(12)
	v_pk_fma_f32 v[90:91], v[56:57], v[136:137], v[90:91]
	v_pk_fma_f32 v[88:89], v[54:55], v[134:135], v[88:89]
	v_pk_fma_f32 v[90:91], v[60:61], v[140:141], v[90:91]
	v_pk_fma_f32 v[88:89], v[58:59], v[138:139], v[88:89]
	v_pk_mul_f32 v[0:1], v[0:1], v[216:217]
	v_pk_fma_f32 v[88:89], v[62:63], v[142:143], v[88:89]
	v_pk_mul_f32 v[2:3], v[2:3], v[218:219]
	v_pk_add_f32 v[88:89], v[90:91], v[88:89]
	v_pk_mul_f32 v[4:5], v[4:5], v[220:221]
	v_add_f32_e32 v206, v88, v89
	ds_read_b128 v[88:91], v207 offset:640
	ds_read_b128 v[92:95], v207 offset:896
	ds_read_b128 v[140:143], v204 offset:128
	ds_read_b128 v[136:139], v204 offset:144
	ds_read_b128 v[132:135], v204 offset:160
	ds_read_b128 v[124:127], v204 offset:176
	ds_read_b128 v[96:99], v204 offset:1088
	ds_read_b128 v[100:103], v204 offset:1104
	ds_read_b128 v[104:107], v204 offset:1120
	ds_read_b128 v[108:111], v204 offset:1136
	v_pk_mul_f32 v[6:7], v[6:7], v[222:223]
	s_waitcnt lgkmcnt(11)
	v_pk_mul_f32 v[8:9], v[8:9], v[224:225]
	v_pk_mul_f32 v[10:11], v[10:11], v[226:227]
	v_pk_mul_f32 v[12:13], v[12:13], v[228:229]
	v_pk_mul_f32 v[14:15], v[14:15], v[230:231]
	v_fmac_f32_dpp v0, v208, v206 quad_perm:[0,0,0,0] row_mask:0xf bank_mask:0xf
	v_fmac_f32_dpp v1, v209, v206 quad_perm:[0,0,0,0] row_mask:0xf bank_mask:0xf
	v_fmac_f32_dpp v2, v210, v206 quad_perm:[0,0,0,0] row_mask:0xf bank_mask:0xf
	v_fmac_f32_dpp v3, v211, v206 quad_perm:[0,0,0,0] row_mask:0xf bank_mask:0xf
	v_fmac_f32_dpp v4, v208, v206 quad_perm:[1,1,1,1] row_mask:0xf bank_mask:0xf
	v_fmac_f32_dpp v5, v209, v206 quad_perm:[1,1,1,1] row_mask:0xf bank_mask:0xf
	v_fmac_f32_dpp v6, v210, v206 quad_perm:[1,1,1,1] row_mask:0xf bank_mask:0xf
	v_fmac_f32_dpp v7, v211, v206 quad_perm:[1,1,1,1] row_mask:0xf bank_mask:0xf
	v_fmac_f32_dpp v8, v208, v206 quad_perm:[2,2,2,2] row_mask:0xf bank_mask:0xf
	v_fmac_f32_dpp v9, v209, v206 quad_perm:[2,2,2,2] row_mask:0xf bank_mask:0xf
	v_fmac_f32_dpp v10, v210, v206 quad_perm:[2,2,2,2] row_mask:0xf bank_mask:0xf
	v_fmac_f32_dpp v11, v211, v206 quad_perm:[2,2,2,2] row_mask:0xf bank_mask:0xf
	v_fmac_f32_dpp v12, v208, v206 quad_perm:[3,3,3,3] row_mask:0xf bank_mask:0xf
	v_fmac_f32_dpp v13, v209, v206 quad_perm:[3,3,3,3] row_mask:0xf bank_mask:0xf
	v_fmac_f32_dpp v14, v210, v206 quad_perm:[3,3,3,3] row_mask:0xf bank_mask:0xf
	v_fmac_f32_dpp v15, v211, v206 quad_perm:[3,3,3,3] row_mask:0xf bank_mask:0xf
	v_fmac_f32_dpp v0, v212, v205 quad_perm:[0,0,0,0] row_mask:0xf bank_mask:0xf
	v_fmac_f32_dpp v1, v213, v205 quad_perm:[0,0,0,0] row_mask:0xf bank_mask:0xf
	v_fmac_f32_dpp v2, v214, v205 quad_perm:[0,0,0,0] row_mask:0xf bank_mask:0xf
	v_fmac_f32_dpp v3, v215, v205 quad_perm:[0,0,0,0] row_mask:0xf bank_mask:0xf
	v_fmac_f32_dpp v4, v212, v205 quad_perm:[1,1,1,1] row_mask:0xf bank_mask:0xf
	v_fmac_f32_dpp v5, v213, v205 quad_perm:[1,1,1,1] row_mask:0xf bank_mask:0xf
	v_fmac_f32_dpp v6, v214, v205 quad_perm:[1,1,1,1] row_mask:0xf bank_mask:0xf
	v_fmac_f32_dpp v7, v215, v205 quad_perm:[1,1,1,1] row_mask:0xf bank_mask:0xf
	v_fmac_f32_dpp v8, v212, v205 quad_perm:[2,2,2,2] row_mask:0xf bank_mask:0xf
	v_fmac_f32_dpp v9, v213, v205 quad_perm:[2,2,2,2] row_mask:0xf bank_mask:0xf
	v_fmac_f32_dpp v10, v214, v205 quad_perm:[2,2,2,2] row_mask:0xf bank_mask:0xf
	v_fmac_f32_dpp v11, v215, v205 quad_perm:[2,2,2,2] row_mask:0xf bank_mask:0xf
	v_fmac_f32_dpp v12, v212, v205 quad_perm:[3,3,3,3] row_mask:0xf bank_mask:0xf
	v_fmac_f32_dpp v13, v213, v205 quad_perm:[3,3,3,3] row_mask:0xf bank_mask:0xf
	v_fmac_f32_dpp v14, v214, v205 quad_perm:[3,3,3,3] row_mask:0xf bank_mask:0xf
	v_fmac_f32_dpp v15, v215, v205 quad_perm:[3,3,3,3] row_mask:0xf bank_mask:0xf
	v_pk_mul_f32 v[16:17], v[16:17], v[128:129]
	v_pk_mul_f32 v[18:19], v[18:19], v[130:131]
	v_pk_mul_f32 v[20:21], v[20:21], v[120:121]
	v_pk_mul_f32 v[22:23], v[22:23], v[122:123]
	v_pk_mul_f32 v[24:25], v[24:25], v[116:117]
	v_pk_mul_f32 v[26:27], v[26:27], v[118:119]
	v_pk_mul_f32 v[28:29], v[28:29], v[112:113]
	v_pk_mul_f32 v[30:31], v[30:31], v[114:115]
	v_pk_fma_f32 v[76:77], v[76:77], v[0:1], 0 op_sel_hi:[1,1,0]
	v_fmac_f32_dpp v16, v68, v206 quad_perm:[0,0,0,0] row_mask:0xf bank_mask:0xf
	v_fmac_f32_dpp v17, v69, v206 quad_perm:[0,0,0,0] row_mask:0xf bank_mask:0xf
	v_fmac_f32_dpp v18, v70, v206 quad_perm:[0,0,0,0] row_mask:0xf bank_mask:0xf
	v_fmac_f32_dpp v19, v71, v206 quad_perm:[0,0,0,0] row_mask:0xf bank_mask:0xf
	v_fmac_f32_dpp v20, v68, v206 quad_perm:[1,1,1,1] row_mask:0xf bank_mask:0xf
	v_pk_fma_f32 v[76:77], v[80:81], v[4:5], v[76:77]
	v_fmac_f32_dpp v21, v69, v206 quad_perm:[1,1,1,1] row_mask:0xf bank_mask:0xf
	v_fmac_f32_dpp v22, v70, v206 quad_perm:[1,1,1,1] row_mask:0xf bank_mask:0xf
	v_fmac_f32_dpp v23, v71, v206 quad_perm:[1,1,1,1] row_mask:0xf bank_mask:0xf
	v_fmac_f32_dpp v24, v68, v206 quad_perm:[2,2,2,2] row_mask:0xf bank_mask:0xf
	v_fmac_f32_dpp v25, v69, v206 quad_perm:[2,2,2,2] row_mask:0xf bank_mask:0xf
	v_fmac_f32_dpp v26, v70, v206 quad_perm:[2,2,2,2] row_mask:0xf bank_mask:0xf
	v_fmac_f32_dpp v27, v71, v206 quad_perm:[2,2,2,2] row_mask:0xf bank_mask:0xf
	v_fmac_f32_dpp v28, v68, v206 quad_perm:[3,3,3,3] row_mask:0xf bank_mask:0xf
	v_fmac_f32_dpp v29, v69, v206 quad_perm:[3,3,3,3] row_mask:0xf bank_mask:0xf
	v_fmac_f32_dpp v30, v70, v206 quad_perm:[3,3,3,3] row_mask:0xf bank_mask:0xf
	v_fmac_f32_dpp v31, v71, v206 quad_perm:[3,3,3,3] row_mask:0xf bank_mask:0xf
	v_pk_fma_f32 v[76:77], v[84:85], v[8:9], v[76:77]
	v_fmac_f32_dpp v16, v72, v205 quad_perm:[0,0,0,0] row_mask:0xf bank_mask:0xf
	v_fmac_f32_dpp v17, v73, v205 quad_perm:[0,0,0,0] row_mask:0xf bank_mask:0xf
	v_fmac_f32_dpp v18, v74, v205 quad_perm:[0,0,0,0] row_mask:0xf bank_mask:0xf
	v_fmac_f32_dpp v19, v75, v205 quad_perm:[0,0,0,0] row_mask:0xf bank_mask:0xf
	v_fmac_f32_dpp v20, v72, v205 quad_perm:[1,1,1,1] row_mask:0xf bank_mask:0xf
	v_fmac_f32_dpp v21, v73, v205 quad_perm:[1,1,1,1] row_mask:0xf bank_mask:0xf
	v_fmac_f32_dpp v22, v74, v205 quad_perm:[1,1,1,1] row_mask:0xf bank_mask:0xf
	v_fmac_f32_dpp v23, v75, v205 quad_perm:[1,1,1,1] row_mask:0xf bank_mask:0xf
	v_fmac_f32_dpp v24, v72, v205 quad_perm:[2,2,2,2] row_mask:0xf bank_mask:0xf
	v_fmac_f32_dpp v25, v73, v205 quad_perm:[2,2,2,2] row_mask:0xf bank_mask:0xf
	v_fmac_f32_dpp v26, v74, v205 quad_perm:[2,2,2,2] row_mask:0xf bank_mask:0xf
	v_fmac_f32_dpp v27, v75, v205 quad_perm:[2,2,2,2] row_mask:0xf bank_mask:0xf
	v_fmac_f32_dpp v28, v72, v205 quad_perm:[3,3,3,3] row_mask:0xf bank_mask:0xf
	v_fmac_f32_dpp v29, v73, v205 quad_perm:[3,3,3,3] row_mask:0xf bank_mask:0xf
	v_fmac_f32_dpp v30, v74, v205 quad_perm:[3,3,3,3] row_mask:0xf bank_mask:0xf
	v_fmac_f32_dpp v31, v75, v205 quad_perm:[3,3,3,3] row_mask:0xf bank_mask:0xf
	ds_read_b128 v[68:71], v207 offset:704
	ds_read_b128 v[72:75], v207 offset:960
	ds_read_b128 v[120:123], v204 offset:192
	ds_read_b128 v[128:131], v204 offset:208
	ds_read_b128 v[208:211], v204 offset:224
	ds_read_b128 v[212:215], v204 offset:240
	s_waitcnt lgkmcnt(14)
	v_pk_fma_f32 v[64:65], v[64:65], v[12:13], v[76:77]
	v_pk_fma_f32 v[76:77], v[78:79], v[2:3], 0 op_sel_hi:[1,1,0]
	ds_read_b128 v[112:115], v204 offset:1184
	v_pk_fma_f32 v[76:77], v[82:83], v[6:7], v[76:77]
	ds_read_b128 v[78:81], v204 offset:1152
	ds_read_b128 v[82:85], v204 offset:1168
	ds_read_b128 v[116:119], v204 offset:1200
	v_pk_fma_f32 v[76:77], v[86:87], v[10:11], v[76:77]
	s_waitcnt lgkmcnt(14)
	v_pk_mul_f32 v[32:33], v[32:33], v[140:141]
	v_pk_fma_f32 v[66:67], v[66:67], v[14:15], v[76:77]
	v_pk_mul_f32 v[34:35], v[34:35], v[142:143]
	v_pk_mul_f32 v[36:37], v[36:37], v[136:137]
	v_pk_mul_f32 v[38:39], v[38:39], v[138:139]
	v_pk_mul_f32 v[40:41], v[40:41], v[132:133]
	v_pk_mul_f32 v[42:43], v[42:43], v[134:135]
	v_pk_mul_f32 v[44:45], v[44:45], v[124:125]
	v_pk_mul_f32 v[46:47], v[46:47], v[126:127]
	ds_read_b128 v[124:127], v204 offset:1216
	ds_read_b128 v[132:135], v204 offset:1232
	ds_read_b128 v[136:139], v204 offset:1248
	ds_read_b128 v[140:143], v204 offset:1264
	s_waitcnt lgkmcnt(4)
	v_pk_fma_f32 v[64:65], v[96:97], v[16:17], v[64:65]
	v_pk_fma_f32 v[66:67], v[98:99], v[18:19], v[66:67]
	v_pk_fma_f32 v[64:65], v[100:101], v[20:21], v[64:65]
	v_pk_fma_f32 v[66:67], v[102:103], v[22:23], v[66:67]
	v_pk_fma_f32 v[64:65], v[104:105], v[24:25], v[64:65]
	v_pk_fma_f32 v[66:67], v[106:107], v[26:27], v[66:67]
	v_pk_fma_f32 v[64:65], v[108:109], v[28:29], v[64:65]
	v_fmac_f32_dpp v32, v88, v206 quad_perm:[0,0,0,0] row_mask:0xf bank_mask:0xf
	v_fmac_f32_dpp v33, v89, v206 quad_perm:[0,0,0,0] row_mask:0xf bank_mask:0xf
	v_fmac_f32_dpp v34, v90, v206 quad_perm:[0,0,0,0] row_mask:0xf bank_mask:0xf
	v_fmac_f32_dpp v35, v91, v206 quad_perm:[0,0,0,0] row_mask:0xf bank_mask:0xf
	v_fmac_f32_dpp v36, v88, v206 quad_perm:[1,1,1,1] row_mask:0xf bank_mask:0xf
	v_fmac_f32_dpp v37, v89, v206 quad_perm:[1,1,1,1] row_mask:0xf bank_mask:0xf
	v_fmac_f32_dpp v38, v90, v206 quad_perm:[1,1,1,1] row_mask:0xf bank_mask:0xf
	v_fmac_f32_dpp v39, v91, v206 quad_perm:[1,1,1,1] row_mask:0xf bank_mask:0xf
	v_fmac_f32_dpp v40, v88, v206 quad_perm:[2,2,2,2] row_mask:0xf bank_mask:0xf
	v_fmac_f32_dpp v41, v89, v206 quad_perm:[2,2,2,2] row_mask:0xf bank_mask:0xf
	v_fmac_f32_dpp v42, v90, v206 quad_perm:[2,2,2,2] row_mask:0xf bank_mask:0xf
	v_fmac_f32_dpp v43, v91, v206 quad_perm:[2,2,2,2] row_mask:0xf bank_mask:0xf
	v_fmac_f32_dpp v44, v88, v206 quad_perm:[3,3,3,3] row_mask:0xf bank_mask:0xf
	v_fmac_f32_dpp v45, v89, v206 quad_perm:[3,3,3,3] row_mask:0xf bank_mask:0xf
	v_fmac_f32_dpp v46, v90, v206 quad_perm:[3,3,3,3] row_mask:0xf bank_mask:0xf
	v_fmac_f32_dpp v47, v91, v206 quad_perm:[3,3,3,3] row_mask:0xf bank_mask:0xf
	v_pk_fma_f32 v[86:87], v[110:111], v[30:31], v[66:67]
	v_fmac_f32_dpp v32, v92, v205 quad_perm:[0,0,0,0] row_mask:0xf bank_mask:0xf
	v_fmac_f32_dpp v33, v93, v205 quad_perm:[0,0,0,0] row_mask:0xf bank_mask:0xf
	v_fmac_f32_dpp v34, v94, v205 quad_perm:[0,0,0,0] row_mask:0xf bank_mask:0xf
	v_fmac_f32_dpp v35, v95, v205 quad_perm:[0,0,0,0] row_mask:0xf bank_mask:0xf
	v_fmac_f32_dpp v36, v92, v205 quad_perm:[1,1,1,1] row_mask:0xf bank_mask:0xf
	v_fmac_f32_dpp v37, v93, v205 quad_perm:[1,1,1,1] row_mask:0xf bank_mask:0xf
	v_fmac_f32_dpp v38, v94, v205 quad_perm:[1,1,1,1] row_mask:0xf bank_mask:0xf
	v_fmac_f32_dpp v39, v95, v205 quad_perm:[1,1,1,1] row_mask:0xf bank_mask:0xf
	v_fmac_f32_dpp v40, v92, v205 quad_perm:[2,2,2,2] row_mask:0xf bank_mask:0xf
	v_fmac_f32_dpp v41, v93, v205 quad_perm:[2,2,2,2] row_mask:0xf bank_mask:0xf
	v_fmac_f32_dpp v42, v94, v205 quad_perm:[2,2,2,2] row_mask:0xf bank_mask:0xf
	v_fmac_f32_dpp v43, v95, v205 quad_perm:[2,2,2,2] row_mask:0xf bank_mask:0xf
	v_fmac_f32_dpp v44, v92, v205 quad_perm:[3,3,3,3] row_mask:0xf bank_mask:0xf
	v_fmac_f32_dpp v45, v93, v205 quad_perm:[3,3,3,3] row_mask:0xf bank_mask:0xf
	v_fmac_f32_dpp v46, v94, v205 quad_perm:[3,3,3,3] row_mask:0xf bank_mask:0xf
	v_fmac_f32_dpp v47, v95, v205 quad_perm:[3,3,3,3] row_mask:0xf bank_mask:0xf
	v_pk_fma_f32 v[64:65], v[78:79], v[32:33], v[64:65]
	v_pk_mul_f32 v[48:49], v[48:49], v[120:121]
	v_pk_mul_f32 v[50:51], v[50:51], v[122:123]
	v_pk_mul_f32 v[52:53], v[52:53], v[128:129]
	v_pk_mul_f32 v[54:55], v[54:55], v[130:131]
	v_pk_mul_f32 v[56:57], v[56:57], v[208:209]
	v_pk_mul_f32 v[58:59], v[58:59], v[210:211]
	v_pk_mul_f32 v[60:61], v[60:61], v[212:213]
	v_pk_mul_f32 v[62:63], v[62:63], v[214:215]
	v_pk_fma_f32 v[64:65], v[82:83], v[36:37], v[64:65]
	v_fmac_f32_dpp v48, v68, v206 quad_perm:[0,0,0,0] row_mask:0xf bank_mask:0xf
	v_fmac_f32_dpp v49, v69, v206 quad_perm:[0,0,0,0] row_mask:0xf bank_mask:0xf
	v_fmac_f32_dpp v50, v70, v206 quad_perm:[0,0,0,0] row_mask:0xf bank_mask:0xf
	v_fmac_f32_dpp v51, v71, v206 quad_perm:[0,0,0,0] row_mask:0xf bank_mask:0xf
	v_fmac_f32_dpp v52, v68, v206 quad_perm:[1,1,1,1] row_mask:0xf bank_mask:0xf
	v_pk_fma_f32 v[64:65], v[112:113], v[40:41], v[64:65]
	v_fmac_f32_dpp v53, v69, v206 quad_perm:[1,1,1,1] row_mask:0xf bank_mask:0xf
	v_fmac_f32_dpp v54, v70, v206 quad_perm:[1,1,1,1] row_mask:0xf bank_mask:0xf
	v_fmac_f32_dpp v55, v71, v206 quad_perm:[1,1,1,1] row_mask:0xf bank_mask:0xf
	v_fmac_f32_dpp v56, v68, v206 quad_perm:[2,2,2,2] row_mask:0xf bank_mask:0xf
	v_fmac_f32_dpp v57, v69, v206 quad_perm:[2,2,2,2] row_mask:0xf bank_mask:0xf
	v_fmac_f32_dpp v58, v70, v206 quad_perm:[2,2,2,2] row_mask:0xf bank_mask:0xf
	v_fmac_f32_dpp v59, v71, v206 quad_perm:[2,2,2,2] row_mask:0xf bank_mask:0xf
	v_fmac_f32_dpp v60, v68, v206 quad_perm:[3,3,3,3] row_mask:0xf bank_mask:0xf
	v_fmac_f32_dpp v61, v69, v206 quad_perm:[3,3,3,3] row_mask:0xf bank_mask:0xf
	v_fmac_f32_dpp v62, v70, v206 quad_perm:[3,3,3,3] row_mask:0xf bank_mask:0xf
	v_fmac_f32_dpp v63, v71, v206 quad_perm:[3,3,3,3] row_mask:0xf bank_mask:0xf
	v_pk_fma_f32 v[96:97], v[116:117], v[44:45], v[64:65]
	v_fmac_f32_dpp v48, v72, v205 quad_perm:[0,0,0,0] row_mask:0xf bank_mask:0xf
	v_fmac_f32_dpp v49, v73, v205 quad_perm:[0,0,0,0] row_mask:0xf bank_mask:0xf
	v_fmac_f32_dpp v50, v74, v205 quad_perm:[0,0,0,0] row_mask:0xf bank_mask:0xf
	v_fmac_f32_dpp v51, v75, v205 quad_perm:[0,0,0,0] row_mask:0xf bank_mask:0xf
	v_fmac_f32_dpp v52, v72, v205 quad_perm:[1,1,1,1] row_mask:0xf bank_mask:0xf
	v_fmac_f32_dpp v53, v73, v205 quad_perm:[1,1,1,1] row_mask:0xf bank_mask:0xf
	v_fmac_f32_dpp v54, v74, v205 quad_perm:[1,1,1,1] row_mask:0xf bank_mask:0xf
	v_fmac_f32_dpp v55, v75, v205 quad_perm:[1,1,1,1] row_mask:0xf bank_mask:0xf
	v_fmac_f32_dpp v56, v72, v205 quad_perm:[2,2,2,2] row_mask:0xf bank_mask:0xf
	v_fmac_f32_dpp v57, v73, v205 quad_perm:[2,2,2,2] row_mask:0xf bank_mask:0xf
	v_fmac_f32_dpp v58, v74, v205 quad_perm:[2,2,2,2] row_mask:0xf bank_mask:0xf
	v_fmac_f32_dpp v59, v75, v205 quad_perm:[2,2,2,2] row_mask:0xf bank_mask:0xf
	v_fmac_f32_dpp v60, v72, v205 quad_perm:[3,3,3,3] row_mask:0xf bank_mask:0xf
	v_fmac_f32_dpp v61, v73, v205 quad_perm:[3,3,3,3] row_mask:0xf bank_mask:0xf
	v_fmac_f32_dpp v62, v74, v205 quad_perm:[3,3,3,3] row_mask:0xf bank_mask:0xf
	v_fmac_f32_dpp v63, v75, v205 quad_perm:[3,3,3,3] row_mask:0xf bank_mask:0xf
	ds_read_b128 v[72:75], v204 offset:1824
	ds_read_b128 v[76:79], v204 offset:1840
	ds_read_b128 v[88:91], v204 offset:1888
	ds_read_b128 v[92:95], v204 offset:1904
	v_pk_fma_f32 v[80:81], v[80:81], v[34:35], v[86:87]
	ds_read_b128 v[64:67], v204 offset:1792
	v_pk_fma_f32 v[80:81], v[84:85], v[38:39], v[80:81]
	ds_read_b128 v[68:71], v204 offset:1808
	v_pk_fma_f32 v[80:81], v[114:115], v[42:43], v[80:81]
	ds_read_b128 v[84:87], v204 offset:1872
	v_pk_fma_f32 v[98:99], v[118:119], v[46:47], v[80:81]
	ds_read_b128 v[80:83], v204 offset:1856
	s_waitcnt lgkmcnt(8)
	v_pk_fma_f32 v[96:97], v[124:125], v[48:49], v[96:97]
	v_pk_fma_f32 v[98:99], v[126:127], v[50:51], v[98:99]
	v_pk_fma_f32 v[96:97], v[132:133], v[52:53], v[96:97]
	v_pk_fma_f32 v[98:99], v[134:135], v[54:55], v[98:99]
	v_pk_fma_f32 v[96:97], v[136:137], v[56:57], v[96:97]
	v_pk_fma_f32 v[98:99], v[138:139], v[58:59], v[98:99]
	v_pk_fma_f32 v[96:97], v[140:141], v[60:61], v[96:97]
	v_pk_fma_f32 v[98:99], v[142:143], v[62:63], v[98:99]
	v_add_u32_e32 v102, s1, v152
	v_pk_add_f32 v[96:97], v[96:97], v[98:99]
	s_addk_i32 s1, 0x100
	v_add_u32_e32 v204, 0x600, v204
	s_cmpk_lg_i32 s1, 0x800
	v_add_f32_e32 v96, v96, v97
	ds_write_b32 v102, v96
	s_cbranch_scc1 .Lcons_short_loop
	s_branch .LBB0_384
